# plus weight-conversion loops with norm gain (gate/up/w_in): 8 row loads + 8 gain loads issued together, one wait, then scale and stage
# speedup vs baseline: 1.0554x; 1.0208x over previous
; #define LAS __attribute__((address_space(3)))
; __device__ __forceinline__ void transpose_item(const float* W, int N, const float* gain, bf16* WT, int ldt, int k0, int n0, int drow, LAS float* scr, int lane) {
;     ...
;     for (int i = 0; i < 8; ++i) { const int kk = kq + 8 * i; f32x4 v = *(const f32x4*)(W + (size_t)(k0 + kk) * N + n0 + n4); if (gain) v = v * gain[k0 + kk];
;         LAS float* sp = scr + kk * 33 + n4; sp[0] = v.x; sp[1] = v.y; sp[2] = v.z; sp[3] = v.w; }
.LBB0_560:
	s_mul_hi_i32 s23, s12, 0x2e8ba2e9
	s_lshr_b32 s25, s23, 31
	s_ashr_i32 s23, s23, 4
	s_add_i32 s23, s23, s25
	s_mul_i32 s25, s23, 0xfffff500
	s_add_i32 s54, s15, s25
	s_lshl_b32 s52, s23, 6
	s_ashr_i32 s55, s54, 31
	v_lshl_add_u64 v[26:27], s[54:55], 2, v[22:23]
	v_or_b32_e32 v4, s52, v0
	v_mad_i64_i32 v[6:7], s[26:27], v4, s31, v[26:27]
	global_load_dwordx4 v[84:87], v[6:7], off
	v_or_b32_e32 v4, s52, v30
	v_mad_i64_i32 v[6:7], s[26:27], v4, s31, v[26:27]
	global_load_dwordx4 v[88:91], v[6:7], off
	v_or_b32_e32 v4, s52, v31
	v_mad_i64_i32 v[6:7], s[26:27], v4, s31, v[26:27]
	global_load_dwordx4 v[92:95], v[6:7], off
	v_or_b32_e32 v4, s52, v32
	v_mad_i64_i32 v[6:7], s[26:27], v4, s31, v[26:27]
	global_load_dwordx4 v[96:99], v[6:7], off
	v_or_b32_e32 v4, s52, v33
	v_mad_i64_i32 v[6:7], s[26:27], v4, s31, v[26:27]
	global_load_dwordx4 v[100:103], v[6:7], off
	v_or_b32_e32 v4, s52, v34
	v_mad_i64_i32 v[6:7], s[26:27], v4, s31, v[26:27]
	global_load_dwordx4 v[104:107], v[6:7], off
	v_or_b32_e32 v4, s52, v35
	v_mad_i64_i32 v[6:7], s[26:27], v4, s31, v[26:27]
	global_load_dwordx4 v[108:111], v[6:7], off
	v_or_b32_e32 v4, s52, v36
	v_mad_i64_i32 v[6:7], s[26:27], v4, s31, v[26:27]
	global_load_dwordx4 v[112:115], v[6:7], off
	s_ashr_i32 s53, s52, 31
	s_and_b64 vcc, exec, s[50:51]
	s_cbranch_vccz .Lconv_nog_0
	v_lshl_add_u64 v[6:7], s[52:53], 0, v[0:1]
	v_lshl_add_u64 v[6:7], v[6:7], 2, s[44:45]
	global_load_dword v116, v[6:7], off offset:0
	global_load_dword v118, v[6:7], off offset:32
	global_load_dword v120, v[6:7], off offset:64
	global_load_dword v122, v[6:7], off offset:96
	global_load_dword v124, v[6:7], off offset:128
	global_load_dword v126, v[6:7], off offset:160
	global_load_dword v128, v[6:7], off offset:192
	global_load_dword v130, v[6:7], off offset:224
	s_waitcnt vmcnt(0)
	v_pk_mul_f32 v[84:85], v[84:85], v[116:117] op_sel_hi:[1,0]
	v_pk_mul_f32 v[86:87], v[86:87], v[116:117] op_sel_hi:[1,0]
	v_pk_mul_f32 v[88:89], v[88:89], v[118:119] op_sel_hi:[1,0]
	v_pk_mul_f32 v[90:91], v[90:91], v[118:119] op_sel_hi:[1,0]
	v_pk_mul_f32 v[92:93], v[92:93], v[120:121] op_sel_hi:[1,0]
	v_pk_mul_f32 v[94:95], v[94:95], v[120:121] op_sel_hi:[1,0]
	v_pk_mul_f32 v[96:97], v[96:97], v[122:123] op_sel_hi:[1,0]
	v_pk_mul_f32 v[98:99], v[98:99], v[122:123] op_sel_hi:[1,0]
	v_pk_mul_f32 v[100:101], v[100:101], v[124:125] op_sel_hi:[1,0]
	v_pk_mul_f32 v[102:103], v[102:103], v[124:125] op_sel_hi:[1,0]
	v_pk_mul_f32 v[104:105], v[104:105], v[126:127] op_sel_hi:[1,0]
	v_pk_mul_f32 v[106:107], v[106:107], v[126:127] op_sel_hi:[1,0]
	v_pk_mul_f32 v[108:109], v[108:109], v[128:129] op_sel_hi:[1,0]
	v_pk_mul_f32 v[110:111], v[110:111], v[128:129] op_sel_hi:[1,0]
	v_pk_mul_f32 v[112:113], v[112:113], v[130:131] op_sel_hi:[1,0]
	v_pk_mul_f32 v[114:115], v[114:115], v[130:131] op_sel_hi:[1,0]
.Lconv_nog_0:
	s_waitcnt vmcnt(0)
	v_add_u32_e32 v4, v28, v29
	ds_write2_b32 v4, v84, v85 offset1:1
	ds_write2_b32 v4, v86, v87 offset0:2 offset1:3
	v_add_u32_e32 v4, v28, v38
	ds_write2_b32 v4, v88, v89 offset1:1
	ds_write2_b32 v4, v90, v91 offset0:2 offset1:3
	v_add_u32_e32 v2, v28, v39
	ds_write2_b32 v2, v92, v93 offset1:1
	ds_write2_b32 v2, v94, v95 offset0:2 offset1:3
	v_add_u32_e32 v4, 0x420, v2
	ds_write2_b32 v4, v96, v97 offset1:1
	ds_write2_b32 v4, v98, v99 offset0:2 offset1:3
	v_add_u32_e32 v4, 0x840, v2
	ds_write2_b32 v4, v100, v101 offset1:1
	ds_write2_b32 v4, v102, v103 offset0:2 offset1:3
	v_add_u32_e32 v4, 0xc60, v2
	ds_write2_b32 v4, v104, v105 offset1:1
	ds_write2_b32 v4, v106, v107 offset0:2 offset1:3
	v_add_u32_e32 v4, 0x1080, v2
	ds_write2_b32 v4, v108, v109 offset1:1
	ds_write2_b32 v4, v110, v111 offset0:2 offset1:3
	v_mov_b64_e32 v[8:9], v[112:113]
	v_mov_b64_e32 v[10:11], v[114:115]
	s_branch .LBB0_559

; #define LAS __attribute__((address_space(3)))
; __device__ __forceinline__ void transpose_item(const float* W, int N, const float* gain, bf16* WT, int ldt, int k0, int n0, int drow, LAS float* scr, int lane) {
;     ...
;     for (int i = 0; i < 8; ++i) { const int kk = kq + 8 * i; f32x4 v = *(const f32x4*)(W + (size_t)(k0 + kk) * N + n0 + n4); if (gain) v = v * gain[k0 + kk];
;         LAS float* sp = scr + kk * 33 + n4; sp[0] = v.x; sp[1] = v.y; sp[2] = v.z; sp[3] = v.w; }
.LBB0_581:
	s_mul_hi_i32 s23, s12, 0x2e8ba2e9
	s_lshr_b32 s25, s23, 31
	s_ashr_i32 s23, s23, 4
	s_add_i32 s23, s23, s25
	s_mul_i32 s25, s23, 0xfffff500
	s_add_i32 s50, s15, s25
	s_lshl_b32 s48, s23, 6
	s_ashr_i32 s51, s50, 31
	v_lshl_add_u64 v[26:27], s[50:51], 2, v[22:23]
	v_or_b32_e32 v4, s48, v0
	v_mad_i64_i32 v[6:7], s[26:27], v4, s31, v[26:27]
	global_load_dwordx4 v[84:87], v[6:7], off
	v_or_b32_e32 v4, s48, v30
	v_mad_i64_i32 v[6:7], s[26:27], v4, s31, v[26:27]
	global_load_dwordx4 v[88:91], v[6:7], off
	v_or_b32_e32 v4, s48, v31
	v_mad_i64_i32 v[6:7], s[26:27], v4, s31, v[26:27]
	global_load_dwordx4 v[92:95], v[6:7], off
	v_or_b32_e32 v4, s48, v32
	v_mad_i64_i32 v[6:7], s[26:27], v4, s31, v[26:27]
	global_load_dwordx4 v[96:99], v[6:7], off
	v_or_b32_e32 v4, s48, v33
	v_mad_i64_i32 v[6:7], s[26:27], v4, s31, v[26:27]
	global_load_dwordx4 v[100:103], v[6:7], off
	v_or_b32_e32 v4, s48, v34
	v_mad_i64_i32 v[6:7], s[26:27], v4, s31, v[26:27]
	global_load_dwordx4 v[104:107], v[6:7], off
	v_or_b32_e32 v4, s48, v35
	v_mad_i64_i32 v[6:7], s[26:27], v4, s31, v[26:27]
	global_load_dwordx4 v[108:111], v[6:7], off
	v_or_b32_e32 v4, s48, v36
	v_mad_i64_i32 v[6:7], s[26:27], v4, s31, v[26:27]
	global_load_dwordx4 v[112:115], v[6:7], off
	s_ashr_i32 s49, s48, 31
	s_and_b64 vcc, exec, s[46:47]
	s_cbranch_vccz .Lconv_nog_1
	v_lshl_add_u64 v[6:7], s[48:49], 0, v[0:1]
	v_lshl_add_u64 v[6:7], v[6:7], 2, s[44:45]
	global_load_dword v116, v[6:7], off offset:0
	global_load_dword v118, v[6:7], off offset:32
	global_load_dword v120, v[6:7], off offset:64
	global_load_dword v122, v[6:7], off offset:96
	global_load_dword v124, v[6:7], off offset:128
	global_load_dword v126, v[6:7], off offset:160
	global_load_dword v128, v[6:7], off offset:192
	global_load_dword v130, v[6:7], off offset:224
	s_waitcnt vmcnt(0)
	v_pk_mul_f32 v[84:85], v[84:85], v[116:117] op_sel_hi:[1,0]
	v_pk_mul_f32 v[86:87], v[86:87], v[116:117] op_sel_hi:[1,0]
	v_pk_mul_f32 v[88:89], v[88:89], v[118:119] op_sel_hi:[1,0]
	v_pk_mul_f32 v[90:91], v[90:91], v[118:119] op_sel_hi:[1,0]
	v_pk_mul_f32 v[92:93], v[92:93], v[120:121] op_sel_hi:[1,0]
	v_pk_mul_f32 v[94:95], v[94:95], v[120:121] op_sel_hi:[1,0]
	v_pk_mul_f32 v[96:97], v[96:97], v[122:123] op_sel_hi:[1,0]
	v_pk_mul_f32 v[98:99], v[98:99], v[122:123] op_sel_hi:[1,0]
	v_pk_mul_f32 v[100:101], v[100:101], v[124:125] op_sel_hi:[1,0]
	v_pk_mul_f32 v[102:103], v[102:103], v[124:125] op_sel_hi:[1,0]
	v_pk_mul_f32 v[104:105], v[104:105], v[126:127] op_sel_hi:[1,0]
	v_pk_mul_f32 v[106:107], v[106:107], v[126:127] op_sel_hi:[1,0]
	v_pk_mul_f32 v[108:109], v[108:109], v[128:129] op_sel_hi:[1,0]
	v_pk_mul_f32 v[110:111], v[110:111], v[128:129] op_sel_hi:[1,0]
	v_pk_mul_f32 v[112:113], v[112:113], v[130:131] op_sel_hi:[1,0]
	v_pk_mul_f32 v[114:115], v[114:115], v[130:131] op_sel_hi:[1,0]

; #define LAS __attribute__((address_space(3)))
; __device__ __forceinline__ void transpose_item(const float* W, int N, const float* gain, bf16* WT, int ldt, int k0, int n0, int drow, LAS float* scr, int lane) {
;     ...
;     for (int i = 0; i < 8; ++i) { const int kk = kq + 8 * i; f32x4 v = *(const f32x4*)(W + (size_t)(k0 + kk) * N + n0 + n4); if (gain) v = v * gain[k0 + kk];
;         LAS float* sp = scr + kk * 33 + n4; sp[0] = v.x; sp[1] = v.y; sp[2] = v.z; sp[3] = v.w; }
.LBB0_614:
	s_lshl_b32 s42, s20, 6
	s_ashr_i32 s41, s40, 31
	v_lshl_add_u64 v[22:23], s[40:41], 2, v[18:19]
	v_or_b32_e32 v4, s42, v0
	v_mad_i64_i32 v[6:7], s[26:27], v4, s14, v[22:23]
	global_load_dwordx4 v[84:87], v[6:7], off
	v_or_b32_e32 v4, s42, v30
	v_mad_i64_i32 v[6:7], s[26:27], v4, s14, v[22:23]
	global_load_dwordx4 v[88:91], v[6:7], off
	v_or_b32_e32 v4, s42, v31
	v_mad_i64_i32 v[6:7], s[26:27], v4, s14, v[22:23]
	global_load_dwordx4 v[92:95], v[6:7], off
	v_or_b32_e32 v4, s42, v32
	v_mad_i64_i32 v[6:7], s[26:27], v4, s14, v[22:23]
	global_load_dwordx4 v[96:99], v[6:7], off
	v_or_b32_e32 v4, s42, v33
	v_mad_i64_i32 v[6:7], s[26:27], v4, s14, v[22:23]
	global_load_dwordx4 v[100:103], v[6:7], off
	v_or_b32_e32 v4, s42, v34
	v_mad_i64_i32 v[6:7], s[26:27], v4, s14, v[22:23]
	global_load_dwordx4 v[104:107], v[6:7], off
	v_or_b32_e32 v4, s42, v35
	v_mad_i64_i32 v[6:7], s[26:27], v4, s14, v[22:23]
	global_load_dwordx4 v[108:111], v[6:7], off
	v_or_b32_e32 v4, s42, v36
	v_mad_i64_i32 v[6:7], s[26:27], v4, s14, v[22:23]
	global_load_dwordx4 v[112:115], v[6:7], off
	s_ashr_i32 s43, s42, 31
	s_and_b64 vcc, exec, s[38:39]
	s_cbranch_vccz .Lconv_nog_2
	v_lshl_add_u64 v[6:7], s[42:43], 0, v[0:1]
	v_lshl_add_u64 v[6:7], v[6:7], 2, s[36:37]
	global_load_dword v116, v[6:7], off offset:0
	global_load_dword v118, v[6:7], off offset:32
	global_load_dword v120, v[6:7], off offset:64
	global_load_dword v122, v[6:7], off offset:96
	global_load_dword v124, v[6:7], off offset:128
	global_load_dword v126, v[6:7], off offset:160
	global_load_dword v128, v[6:7], off offset:192
	global_load_dword v130, v[6:7], off offset:224
	s_waitcnt vmcnt(0)
	v_pk_mul_f32 v[84:85], v[84:85], v[116:117] op_sel_hi:[1,0]
	v_pk_mul_f32 v[86:87], v[86:87], v[116:117] op_sel_hi:[1,0]
	v_pk_mul_f32 v[88:89], v[88:89], v[118:119] op_sel_hi:[1,0]
	v_pk_mul_f32 v[90:91], v[90:91], v[118:119] op_sel_hi:[1,0]
	v_pk_mul_f32 v[92:93], v[92:93], v[120:121] op_sel_hi:[1,0]
	v_pk_mul_f32 v[94:95], v[94:95], v[120:121] op_sel_hi:[1,0]
	v_pk_mul_f32 v[96:97], v[96:97], v[122:123] op_sel_hi:[1,0]
	v_pk_mul_f32 v[98:99], v[98:99], v[122:123] op_sel_hi:[1,0]
	v_pk_mul_f32 v[100:101], v[100:101], v[124:125] op_sel_hi:[1,0]
	v_pk_mul_f32 v[102:103], v[102:103], v[124:125] op_sel_hi:[1,0]
	v_pk_mul_f32 v[104:105], v[104:105], v[126:127] op_sel_hi:[1,0]
	v_pk_mul_f32 v[106:107], v[106:107], v[126:127] op_sel_hi:[1,0]
	v_pk_mul_f32 v[108:109], v[108:109], v[128:129] op_sel_hi:[1,0]
	v_pk_mul_f32 v[110:111], v[110:111], v[128:129] op_sel_hi:[1,0]
	v_pk_mul_f32 v[112:113], v[112:113], v[130:131] op_sel_hi:[1,0]
	v_pk_mul_f32 v[114:115], v[114:115], v[130:131] op_sel_hi:[1,0]
.Lconv_nog_2:
	s_waitcnt vmcnt(0)
	v_add_u32_e32 v4, v28, v29
	ds_write2_b32 v4, v84, v85 offset1:1
	ds_write2_b32 v4, v86, v87 offset0:2 offset1:3
	v_add_u32_e32 v4, v28, v38
	ds_write2_b32 v4, v88, v89 offset1:1
	ds_write2_b32 v4, v90, v91 offset0:2 offset1:3
	v_add_u32_e32 v17, v28, v39
	ds_write2_b32 v17, v92, v93 offset1:1
	ds_write2_b32 v17, v94, v95 offset0:2 offset1:3
	v_add_u32_e32 v4, 0x420, v17
	ds_write2_b32 v4, v96, v97 offset1:1
	ds_write2_b32 v4, v98, v99 offset0:2 offset1:3
	v_add_u32_e32 v4, 0x840, v17
	ds_write2_b32 v4, v100, v101 offset1:1
	ds_write2_b32 v4, v102, v103 offset0:2 offset1:3
	v_add_u32_e32 v4, 0xc60, v17
	ds_write2_b32 v4, v104, v105 offset1:1
	ds_write2_b32 v4, v106, v107 offset0:2 offset1:3
	v_add_u32_e32 v4, 0x1080, v17
	ds_write2_b32 v4, v108, v109 offset1:1
	ds_write2_b32 v4, v110, v111 offset0:2 offset1:3
	v_mov_b64_e32 v[8:9], v[112:113]
	v_mov_b64_e32 v[10:11], v[114:115]
	s_branch .LBB0_604
